# v009 plus GEMM prologue second wait relaxed vmcnt(6)->vmcnt(8): first MFMA interval no longer waits for the A half-tile it reads one interval later
# baseline (speedup 1.0000x reference)
; #define PG8_STAGE(bufoff, gbase, voff) do { _Pragma("unroll") for (int _i = 0; _i < 2; ++_i) \
;     __builtin_amdgcn_global_load_lds((const unsigned*)((const char*)(gbase) + (voff)[_i]), (LAS unsigned*)(lds + (bufoff) + ldsw + _i * 8192), 16, 0, 0); } while (0)
; #define PG8_WAIT_V(n) asm volatile("s_waitcnt vmcnt(" #n ")" ::: "memory")
; #define PG8_BAR __builtin_amdgcn_s_barrier()
; template <class Epi, bool HOOK>
; __device__ __forceinline__ void gemm_phase(LAS unsigned char* lds, const Gemm g, const StaticOrder& S, const Epi& E, const int hook_t) {
;     ...
;   for (int i = 0; i < 2; ++i) { int R, C; stage_rc(tid * 16 + i * 8192, R, C);
;     voffA[i] = (unsigned)(R * g.lda + C) * 2u; voffB[i] = (unsigned)(R * g.ldb + C) * 2u; }
;   const size_t kstep = (size_t)(BK * 2);
;   const size_t hstepA = (size_t)HALF * g.lda * 2, hstepB = (size_t)HALF * g.ldb * 2;
;   const size_t tstepA = 2 * hstepA, tstepB = 2 * hstepB;
;   const unsigned ldsw = (unsigned)wid * 1024u;
;   const int aoff = lds_byte(wr * 64 + fr, fq * 8), boff = lds_byte(wc * 32 + fr, fq * 8);
;     ...
;   PG8_STAGE(PG8_SB(0, 0), cB, voffB); PG8_STAGE(PG8_SA(0, 0), cA, voffA); PG8_STAGE(PG8_SB(0, 1), cB + hstepB, voffB); PG8_STAGE(PG8_SA(0, 1), cA + hstepA, voffA);
;   if (wr == 1) PG8_BAR;
;   PG8_WAIT_V(4); PG8_BAR;
;   PG8_STAGE(PG8_SB(1, 0), cB + kstep, voffB); PG8_STAGE(PG8_SA(1, 0), cA + kstep, voffA); PG8_STAGE(PG8_SB(1, 1), cB + hstepB + kstep, voffB);
;   PG8_WAIT_V(6); PG8_BAR;
.LBB0_46:
	v_lshrrev_b32_e32 v20, 1, v18
	v_and_b32_e32 v20, 24, v20
	v_and_b32_e32 v19, 15, v18
	v_lshlrev_b32_e32 v21, 1, v20
	v_lshlrev_b32_e32 v18, 2, v18
	s_sext_i32_i8 s18, s0
	v_lshl_or_b32 v156, s1, 6, v19
	v_lshl_or_b32 v19, v19, 6, v21
	s_lshl_b32 s0, s1, 13
	v_and_b32_e32 v18, 32, v18
	v_bitop3_b32 v21, v19, s0, v18 bitop3:0xde
	s_lshl_b32 s0, s4, 5
	s_and_b32 s4, s0, 0x60
	s_add_i32 m0, s28, 0x18000
	v_lshl_add_u64 v[8:9], v[8:9], 0, s[56:57]
	s_lshl_b32 s0, s4, 7
	s_waitcnt vmcnt(2)
	s_barrier
	global_load_lds_dwordx4 v[8:9], off
	v_lshl_add_u64 v[6:7], v[6:7], 0, s[56:57]
	s_add_i32 m0, s28, 0x1a000
	s_add_i32 s34, s28, 0x8000
	s_add_i32 s35, s28, 0xa000
	v_bitop3_b32 v157, v19, s0, v18 bitop3:0xde
	global_load_lds_dwordx4 v[6:7], off
	v_lshl_add_u64 v[4:5], v[4:5], 0, s[56:57]
	s_mov_b32 m0, s34
	s_add_u32 s0, s16, 0x50080
	global_load_lds_dwordx4 v[4:5], off
	v_lshl_add_u64 v[2:3], v[2:3], 0, s[56:57]
	s_mov_b32 m0, s35
	s_addc_u32 s1, s17, 0
	global_load_lds_dwordx4 v[2:3], off
	s_add_i32 m0, s28, 0x1c000
	v_lshl_add_u64 v[2:3], s[0:1], 0, v[0:1]
	global_load_lds_dwordx4 v[2:3], off
	v_lshl_add_u64 v[2:3], s[0:1], 0, v[130:131]
	s_add_i32 m0, s28, 0x1e000
	v_readlane_b32 s0, v252, 31
	global_load_lds_dwordx4 v[2:3], off
	v_or_b32_e32 v158, s4, v20
	s_movk_i32 s4, 0x500
	v_readlane_b32 s1, v252, 32
	v_lshrrev_b32_e32 v3, 1, v10
	v_mul_lo_u32 v2, v12, s4
	s_movk_i32 s5, 0x5000
	s_and_b64 s[0:1], s[0:1], exec
	v_mad_u64_u32 v[2:3], s[0:1], v3, s5, v[2:3]
	v_or_b32_e32 v2, v2, v11
	v_add_lshl_u32 v132, v2, v13, 1
	v_lshrrev_b32_e32 v3, 1, v14
	v_mul_lo_u32 v2, v16, s4
	s_waitcnt vmcnt(8)
	v_mad_u64_u32 v[2:3], s[0:1], v3, s5, v[2:3]
	v_or_b32_e32 v2, v2, v15
	s_cselect_b32 s36, 5, 6
	v_mov_b32_e32 v133, v1
	v_add_lshl_u32 v134, v2, v17, 1
	v_mov_b32_e32 v135, v1
	s_mov_b32 s37, 0
	v_add_u32_e32 v159, 0, v21
	s_barrier
	s_branch .LBB0_48

; #define PG8_STAGE(bufoff, gbase, voff) do { _Pragma("unroll") for (int _i = 0; _i < 2; ++_i) \
;     __builtin_amdgcn_global_load_lds((const unsigned*)((const char*)(gbase) + (voff)[_i]), (LAS unsigned*)(lds + (bufoff) + ldsw + _i * 8192), 16, 0, 0); } while (0)
; #define PG8_WAIT_V(n) asm volatile("s_waitcnt vmcnt(" #n ")" ::: "memory")
; #define PG8_BAR __builtin_amdgcn_s_barrier()
; template <class Epi, bool HOOK>
; __device__ __forceinline__ void gemm_phase(LAS unsigned char* lds, const Gemm g, const StaticOrder& S, const Epi& E, const int hook_t) {
;     ...
;   for (int i = 0; i < 2; ++i) { int R, C; stage_rc(tid * 16 + i * 8192, R, C);
;     voffA[i] = (unsigned)(R * g.lda + C) * 2u; voffB[i] = (unsigned)(R * g.ldb + C) * 2u; }
;   const size_t kstep = (size_t)(BK * 2);
;   const size_t hstepA = (size_t)HALF * g.lda * 2, hstepB = (size_t)HALF * g.ldb * 2;
;   const size_t tstepA = 2 * hstepA, tstepB = 2 * hstepB;
;   const unsigned ldsw = (unsigned)wid * 1024u;
;   const int aoff = lds_byte(wr * 64 + fr, fq * 8), boff = lds_byte(wc * 32 + fr, fq * 8);
;     ...
;   PG8_STAGE(PG8_SB(0, 0), cB, voffB); PG8_STAGE(PG8_SA(0, 0), cA, voffA); PG8_STAGE(PG8_SB(0, 1), cB + hstepB, voffB); PG8_STAGE(PG8_SA(0, 1), cA + hstepA, voffA);
;   if (wr == 1) PG8_BAR;
;   PG8_WAIT_V(4); PG8_BAR;
;   PG8_STAGE(PG8_SB(1, 0), cB + kstep, voffB); PG8_STAGE(PG8_SA(1, 0), cA + kstep, voffA); PG8_STAGE(PG8_SB(1, 1), cB + hstepB + kstep, voffB);
;   PG8_WAIT_V(6); PG8_BAR;
.LBB0_118:
	s_add_u32 s14, s54, s0
	s_addc_u32 s15, s55, s1
	s_add_i32 m0, s31, 0x18000
	v_lshl_add_u64 v[2:3], v[2:3], 0, s[56:57]
	s_waitcnt vmcnt(2)
	s_barrier
	global_load_lds_dwordx4 v[2:3], off
	v_lshl_add_u64 v[2:3], v[4:5], 0, s[56:57]
	s_add_i32 m0, s31, 0x1a000
	s_add_i32 s38, s31, 0x8000
	global_load_lds_dwordx4 v[2:3], off
	v_lshl_add_u64 v[2:3], v[6:7], 0, s[56:57]
	s_mov_b32 m0, s38
	s_add_i32 s39, s31, 0xa000
	global_load_lds_dwordx4 v[2:3], off
	v_lshl_add_u64 v[2:3], v[8:9], 0, s[56:57]
	s_mov_b32 m0, s39
	v_lshrrev_b32_e32 v22, 1, v20
	global_load_lds_dwordx4 v[2:3], off
	s_add_i32 m0, s31, 0x1c000
	v_lshl_add_u64 v[2:3], v[10:11], 0, s[56:57]
	global_load_lds_dwordx4 v[2:3], off
	v_lshl_add_u64 v[2:3], v[12:13], 0, s[56:57]
	s_add_i32 m0, s31, 0x1e000
	v_and_b32_e32 v22, 24, v22
	global_load_lds_dwordx4 v[2:3], off
	v_and_b32_e32 v21, 15, v20
	v_lshlrev_b32_e32 v23, 1, v22
	v_lshlrev_b32_e32 v20, 2, v20
	v_lshl_or_b32 v136, s6, 6, v21
	v_lshl_or_b32 v21, v21, 6, v23
	s_lshl_b32 s0, s6, 13
	v_and_b32_e32 v20, 32, v20
	v_add_u32_e32 v2, v17, v18
	v_bitop3_b32 v23, v21, s0, v20 bitop3:0xde
	s_lshl_b32 s0, s5, 5
	v_add_lshl_u32 v2, v2, v19, 1
	v_mov_b32_e32 v3, v1
	s_and_b32 s0, s0, 0x60
	s_waitcnt vmcnt(8)
	v_lshl_add_u64 v[132:133], s[50:51], 0, v[2:3]
	v_add_u32_e32 v2, v14, v15
	s_lshr_b32 s37, s20, 6
	s_lshl_b32 s1, s0, 7
	v_add_lshl_u32 v2, v2, v16, 1
	s_sext_i32_i16 s43, s4
	v_bitop3_b32 v137, v21, s1, v20 bitop3:0xde
	s_add_i32 s41, s37, -2
	s_mov_b32 s11, s51
	v_or_b32_e32 v138, s0, v22
	v_lshl_add_u64 v[134:135], s[50:51], 0, v[2:3]
	s_mov_b32 s42, 0
	v_add_u32_e32 v139, 0, v23
	s_barrier

; #define PG8_STAGE(bufoff, gbase, voff) do { _Pragma("unroll") for (int _i = 0; _i < 2; ++_i) \
;     __builtin_amdgcn_global_load_lds((const unsigned*)((const char*)(gbase) + (voff)[_i]), (LAS unsigned*)(lds + (bufoff) + ldsw + _i * 8192), 16, 0, 0); } while (0)
; #define PG8_WAIT_V(n) asm volatile("s_waitcnt vmcnt(" #n ")" ::: "memory")
; #define PG8_BAR __builtin_amdgcn_s_barrier()
; template <class Epi, bool HOOK>
; __device__ __forceinline__ void gemm_phase(LAS unsigned char* lds, const Gemm g, const StaticOrder& S, const Epi& E, const int hook_t) {
;     ...
;   for (int i = 0; i < 2; ++i) { int R, C; stage_rc(tid * 16 + i * 8192, R, C);
;     voffA[i] = (unsigned)(R * g.lda + C) * 2u; voffB[i] = (unsigned)(R * g.ldb + C) * 2u; }
;   const size_t kstep = (size_t)(BK * 2);
;   const size_t hstepA = (size_t)HALF * g.lda * 2, hstepB = (size_t)HALF * g.ldb * 2;
;   const size_t tstepA = 2 * hstepA, tstepB = 2 * hstepB;
;   const unsigned ldsw = (unsigned)wid * 1024u;
;   const int aoff = lds_byte(wr * 64 + fr, fq * 8), boff = lds_byte(wc * 32 + fr, fq * 8);
;     ...
;   PG8_STAGE(PG8_SB(0, 0), cB, voffB); PG8_STAGE(PG8_SA(0, 0), cA, voffA); PG8_STAGE(PG8_SB(0, 1), cB + hstepB, voffB); PG8_STAGE(PG8_SA(0, 1), cA + hstepA, voffA);
;   if (wr == 1) PG8_BAR;
;   PG8_WAIT_V(4); PG8_BAR;
;   PG8_STAGE(PG8_SB(1, 0), cB + kstep, voffB); PG8_STAGE(PG8_SA(1, 0), cA + kstep, voffA); PG8_STAGE(PG8_SB(1, 1), cB + hstepB + kstep, voffB);
;   PG8_WAIT_V(6); PG8_BAR;
.LBB0_140:
	s_sext_i32_i8 s17, s4
	v_and_b32_e32 v16, 48, v15
	v_lshlrev_b32_e32 v17, 6, v15
	s_movk_i32 s4, 0x3c0
	v_lshlrev_b32_e32 v15, 2, v15
	s_lshl_b32 s93, s1, 6
	s_lshl_b32 s1, s1, 13
	v_and_or_b32 v16, v17, s4, v16
	v_and_b32_e32 v15, 32, v15
	v_bitop3_b32 v17, v16, s1, v15 bitop3:0xde
	s_lshl_b32 s1, s3, 5
	s_and_b32 s50, s1, 0x60
	s_add_i32 m0, s67, 0x18000
	v_lshl_add_u64 v[8:9], v[8:9], 0, s[56:57]
	s_lshl_b32 s1, s50, 7
	s_waitcnt vmcnt(2)
	s_barrier
	global_load_lds_dwordx4 v[8:9], off
	v_lshl_add_u64 v[6:7], v[6:7], 0, s[56:57]
	s_add_i32 m0, s67, 0x1a000
	s_add_i32 s91, s67, 0x8000
	s_add_i32 s3, s67, 0xa000
	global_load_lds_dwordx4 v[6:7], off
	v_lshl_add_u64 v[4:5], v[4:5], 0, s[56:57]
	s_mov_b32 m0, s91
	s_add_u32 s4, s70, 0x40080
	global_load_lds_dwordx4 v[4:5], off
	v_lshl_add_u64 v[2:3], v[2:3], 0, s[56:57]
	s_mov_b32 m0, s3
	s_addc_u32 s5, s71, 0
	global_load_lds_dwordx4 v[2:3], off
	s_add_i32 m0, s67, 0x1c000
	v_lshl_add_u64 v[2:3], s[4:5], 0, v[154:155]
	global_load_lds_dwordx4 v[2:3], off
	v_lshl_add_u64 v[2:3], s[4:5], 0, v[156:157]
	s_add_i32 m0, s67, 0x1e000
	v_readlane_b32 s4, v252, 31
	global_load_lds_dwordx4 v[2:3], off
	v_lshlrev_b32_e32 v2, 14, v0
	v_and_b32_e32 v2, 0xffff8000, v2
	v_lshl_add_u32 v2, v10, 11, v2
	v_and_b32_e32 v0, 1, v0
	v_lshl_or_b32 v0, v0, 6, v2
	v_lshl_add_u32 v158, v11, 1, v0
	v_lshlrev_b32_e32 v0, 14, v12
	v_and_b32_e32 v0, 0xffff8000, v0
	s_waitcnt vmcnt(8)
	v_readlane_b32 s5, v252, 32
	v_lshl_add_u32 v0, v13, 11, v0
	v_and_b32_e32 v2, 1, v12
	s_and_b64 s[4:5], s[4:5], exec
	v_lshl_or_b32 v0, v2, 6, v0
	v_bitop3_b32 v164, s1, v16, v15 bitop3:0xf6
	s_mov_b32 s1, s51
	s_cselect_b32 s4, 5, 6
	v_mov_b32_e32 v159, v1
	v_lshl_add_u32 v160, v14, 1, v0
	v_mov_b32_e32 v161, v1
	s_mov_b32 s52, 0
	v_add_u32_e32 v165, 0, v17
	s_barrier
	v_writelane_b32 v252, s4, 42
	s_branch .LBB0_142

; #define PG8_STAGE(bufoff, gbase, voff) do { _Pragma("unroll") for (int _i = 0; _i < 2; ++_i) \
;     __builtin_amdgcn_global_load_lds((const unsigned*)((const char*)(gbase) + (voff)[_i]), (LAS unsigned*)(lds + (bufoff) + ldsw + _i * 8192), 16, 0, 0); } while (0)
; #define PG8_WAIT_V(n) asm volatile("s_waitcnt vmcnt(" #n ")" ::: "memory")
; #define PG8_BAR __builtin_amdgcn_s_barrier()
; template <class Epi, bool HOOK>
; __device__ __forceinline__ void gemm_phase(LAS unsigned char* lds, const Gemm g, const StaticOrder& S, const Epi& E, const int hook_t) {
;     ...
;   for (int i = 0; i < 2; ++i) { int R, C; stage_rc(tid * 16 + i * 8192, R, C);
;     voffA[i] = (unsigned)(R * g.lda + C) * 2u; voffB[i] = (unsigned)(R * g.ldb + C) * 2u; }
;   const size_t kstep = (size_t)(BK * 2);
;   const size_t hstepA = (size_t)HALF * g.lda * 2, hstepB = (size_t)HALF * g.ldb * 2;
;   const size_t tstepA = 2 * hstepA, tstepB = 2 * hstepB;
;   const unsigned ldsw = (unsigned)wid * 1024u;
;   const int aoff = lds_byte(wr * 64 + fr, fq * 8), boff = lds_byte(wc * 32 + fr, fq * 8);
;     ...
;   PG8_STAGE(PG8_SB(0, 0), cB, voffB); PG8_STAGE(PG8_SA(0, 0), cA, voffA); PG8_STAGE(PG8_SB(0, 1), cB + hstepB, voffB); PG8_STAGE(PG8_SA(0, 1), cA + hstepA, voffA);
;   if (wr == 1) PG8_BAR;
;   PG8_WAIT_V(4); PG8_BAR;
;   PG8_STAGE(PG8_SB(1, 0), cB + kstep, voffB); PG8_STAGE(PG8_SA(1, 0), cA + kstep, voffA); PG8_STAGE(PG8_SB(1, 1), cB + hstepB + kstep, voffB);
;   PG8_WAIT_V(6); PG8_BAR;
.LBB0_211:
	v_readlane_b32 s1, v252, 33
	s_add_i32 s30, s1, -1
	s_and_b32 s1, s3, 3
	s_add_i32 m0, s19, 0x18000
	v_lshl_add_u64 v[8:9], v[8:9], 0, s[56:57]
	s_lshl_b32 s3, s4, 13
	s_lshl_b32 s5, s1, 12
	s_waitcnt vmcnt(2)
	s_barrier
	global_load_lds_dwordx4 v[8:9], off
	v_lshl_add_u64 v[6:7], v[6:7], 0, s[56:57]
	s_add_i32 m0, s19, 0x1a000
	s_add_i32 s31, s19, 0x8000
	s_add_i32 s34, s19, 0xa000
	global_load_lds_dwordx4 v[6:7], off
	v_lshl_add_u64 v[4:5], v[4:5], 0, s[56:57]
	s_mov_b32 m0, s31
	s_add_u32 s10, s20, 0x40080
	global_load_lds_dwordx4 v[4:5], off
	v_lshl_add_u64 v[2:3], v[2:3], 0, s[56:57]
	s_mov_b32 m0, s34
	s_addc_u32 s11, s21, 0
	global_load_lds_dwordx4 v[2:3], off
	s_add_i32 m0, s19, 0x1c000
	v_lshl_add_u64 v[2:3], s[10:11], 0, v[138:139]
	global_load_lds_dwordx4 v[2:3], off
	v_lshl_add_u64 v[2:3], s[10:11], 0, v[140:141]
	s_add_i32 m0, s19, 0x1e000
	s_lshr_b32 s35, s8, 3
	global_load_lds_dwordx4 v[2:3], off
	v_lshrrev_b32_e32 v2, 1, v0
	v_and_b32_e32 v2, 24, v2
	v_and_b32_e32 v3, 15, v0
	v_lshlrev_b32_e32 v4, 1, v2
	v_lshlrev_b32_e32 v0, 2, v0
	v_lshl_or_b32 v190, s4, 6, v3
	v_lshl_or_b32 v3, v3, 6, v4
	v_and_b32_e32 v0, 32, v0
	v_bitop3_b32 v191, v3, s5, v0 bitop3:0xde
	v_readlane_b32 s4, v253, 55
	v_bitop3_b32 v4, v3, s3, v0 bitop3:0xde
	v_lshlrev_b32_e32 v0, 2, v2
	v_readlane_b32 s5, v253, 56
	v_and_b32_e32 v3, 1, v10
	s_waitcnt vmcnt(8)
	v_lshl_or_b32 v192, s1, 5, v2
	v_lshl_add_u64 v[142:143], s[4:5], 0, v[0:1]
	v_readlane_b32 s4, v253, 57
	v_readlane_b32 s5, v253, 58
	s_lshl_b32 s1, s1, 6
	v_readlane_b32 s3, v253, 59
	v_lshl_add_u64 v[144:145], s[4:5], 0, v[0:1]
	v_lshlrev_b32_e32 v0, 14, v10
	v_and_b32_e32 v0, 0xffff8000, v0
	v_lshl_add_u32 v0, v11, 11, v0
	v_lshl_or_b32 v0, v3, 6, v0
	s_lshl_b32 s4, s78, 10
	v_lshl_add_u32 v146, v12, 1, v0
	v_lshlrev_b32_e32 v0, 14, v13
	s_ashr_i32 s5, s4, 31
	v_and_b32_e32 v0, 0xffff8000, v0
	s_lshl_b64 s[4:5], s[4:5], 2
	v_lshl_add_u32 v0, v14, 11, v0
	v_and_b32_e32 v3, 1, v13
	s_add_u32 s36, s3, s4
	v_readlane_b32 s3, v253, 60
	v_lshl_or_b32 v0, v3, 6, v0
	v_readlane_b32 s52, v252, 25
	s_mov_b32 s9, s51
	s_addc_u32 s37, s3, s5
	v_mov_b32_e32 v147, v1
	v_lshl_add_u32 v148, v15, 1, v0
	v_mov_b32_e32 v149, v1
	s_mov_b32 s38, 0
	v_add_u32_e32 v193, 0, v4
	s_lshl_b32 s39, s1, 1
	v_lshlrev_b32_e32 v150, 1, v2
	v_readlane_b32 s53, v252, 26
	s_barrier
	s_branch .LBB0_213
